# v020_g2epi
# speedup vs baseline: 1.0082x; 1.0082x over previous
; #define SCHED __builtin_amdgcn_sched_barrier(0)
; __device__ __forceinline__ void phase_gemm2(const Params& p, int layer, const float* xold, float* xnew) {
;     ...
; #pragma unroll
;     for (int ai = 0; ai < 2; ++ai)
; #pragma unroll
;       for (int bj = 0; bj < 2; ++bj) {
;         f32x4 xo[4][2];
; #pragma unroll
;         for (int m = 0; m < 4; ++m)
; #pragma unroll
;           for (int n = 0; n < 2; ++n) {
;             int feat = feat0 + ai * 128 + wr * 64 + m * 16 + fq * 4;
;             int tok = tok0 + bj * 128 + wc * 32 + n * 16 + fr;
;             xo[m][n] = *reinterpret_cast<const f32x4*>(xold + (size_t)tok * DM + feat);
;           }
;         SCHED;
; #pragma unroll
;         for (int m = 0; m < 4; ++m)
; #pragma unroll
;           for (int n = 0; n < 2; ++n) {
;             int feat = feat0 + ai * 128 + wr * 64 + m * 16 + fq * 4;
;             int tok = tok0 + bj * 128 + wc * 32 + n * 16 + fr;
;             *reinterpret_cast<f32x4*>(xnew + (size_t)tok * DM + feat) = xo[m][n] + acc[ai][bj][m][n];
.LBB0_34:
	s_or_b64 exec, exec, s[18:19]
	v_lshrrev_b32_e32 v130, 4, v97
	v_lshlrev_b32_e32 v130, 2, v130
	v_lshrrev_b32_e32 v97, 1, v97
	v_and_or_b32 v130, v130, 12, v147
	v_and_b32_e32 v97, 0x60, v97
	v_add_u32_e32 v134, s16, v130
	v_or3_b32 v160, v97, v146, s14
	v_and_b32_e32 v140, 15, v210
	v_bfe_u32 v141, v210, 4, 2
	v_lshrrev_b32_e32 v142, 6, v210
	v_sub_u32_e32 v143, v160, v140
	v_lshlrev_b32_e32 v144, 2, v141
	v_sub_u32_e32 v144, v134, v144
	v_add_u32_e32 v143, v143, v141
	v_lshl_add_u32 v144, v140, 2, v144
	v_lshlrev_b32_e32 v143, 14, v143
	v_lshl_add_u32 v130, v144, 2, v143
	v_add_u32_e32 v131, 0x10000, v130
	v_add_u32_e32 v132, 0x20000, v130
	v_add_u32_e32 v133, 0x30000, v130
	v_add_u32_e32 v134, 0x40000, v130
	v_add_u32_e32 v135, 0x50000, v130
	v_add_u32_e32 v136, 0x60000, v130
	v_add_u32_e32 v137, 0x70000, v130
	v_mul_u32_u24_e32 v142, 0x2200, v142
	v_mul_u32_u24_e32 v145, 0x110, v140
	v_lshl_add_u32 v145, v141, 4, v145
	v_add3_u32 v138, v142, v145, 32
	v_mul_u32_u24_e32 v145, 0x110, v141
	v_lshl_add_u32 v145, v140, 4, v145
	v_add3_u32 v139, v142, v145, 32
	s_mov_b64 s[14:15], s[8:9]
	s_mov_b64 s[16:17], s[10:11]
	ds_write_b128 v138, v[126:129] offset:0
	ds_write_b128 v138, v[122:125] offset:4352
	ds_write_b128 v138, v[118:121] offset:64
	ds_write_b128 v138, v[114:117] offset:4416
	ds_write_b128 v138, v[110:113] offset:128
	ds_write_b128 v138, v[106:109] offset:4480
	ds_write_b128 v138, v[102:105] offset:192
	ds_write_b128 v138, v[98:101] offset:4544
	global_load_dwordx4 v[164:167], v130, s[14:15] offset:0
	global_load_dwordx4 v[168:171], v131, s[14:15] offset:0
	global_load_dwordx4 v[172:175], v132, s[14:15] offset:0
	global_load_dwordx4 v[176:179], v133, s[14:15] offset:0
	global_load_dwordx4 v[180:183], v134, s[14:15] offset:0
	global_load_dwordx4 v[184:187], v135, s[14:15] offset:0
	global_load_dwordx4 v[188:191], v136, s[14:15] offset:0
	global_load_dwordx4 v[192:195], v137, s[14:15] offset:0
	ds_read_b128 v[222:225], v139 offset:0
	ds_read_b128 v[226:229], v139 offset:1088
	ds_read_b128 v[230:233], v139 offset:2176
	ds_read_b128 v[234:237], v139 offset:3264
	ds_read_b128 v[238:241], v139 offset:4352
	ds_read_b128 v[242:245], v139 offset:5440
	ds_read_b128 v[246:249], v139 offset:6528
	ds_read_b128 v[250:253], v139 offset:7616
	s_waitcnt lgkmcnt(0)
	s_waitcnt vmcnt(7)
	v_pk_add_f32 v[222:223], v[222:223], v[164:165]
	v_pk_add_f32 v[224:225], v[224:225], v[166:167]
	global_store_dwordx4 v130, v[222:225], s[16:17] offset:0
	s_waitcnt vmcnt(7)
	v_pk_add_f32 v[226:227], v[226:227], v[168:169]
	v_pk_add_f32 v[228:229], v[228:229], v[170:171]
	global_store_dwordx4 v131, v[226:229], s[16:17] offset:0
	s_waitcnt vmcnt(7)
	v_pk_add_f32 v[230:231], v[230:231], v[172:173]
	v_pk_add_f32 v[232:233], v[232:233], v[174:175]
	global_store_dwordx4 v132, v[230:233], s[16:17] offset:0
	s_waitcnt vmcnt(7)
	v_pk_add_f32 v[234:235], v[234:235], v[176:177]
	v_pk_add_f32 v[236:237], v[236:237], v[178:179]
	global_store_dwordx4 v133, v[234:237], s[16:17] offset:0
	s_waitcnt vmcnt(7)
	v_pk_add_f32 v[238:239], v[238:239], v[180:181]
	v_pk_add_f32 v[240:241], v[240:241], v[182:183]
	global_store_dwordx4 v134, v[238:241], s[16:17] offset:0
	s_waitcnt vmcnt(7)
	v_pk_add_f32 v[242:243], v[242:243], v[184:185]
	v_pk_add_f32 v[244:245], v[244:245], v[186:187]
	global_store_dwordx4 v135, v[242:245], s[16:17] offset:0
	s_waitcnt vmcnt(7)
	v_pk_add_f32 v[246:247], v[246:247], v[188:189]
	v_pk_add_f32 v[248:249], v[248:249], v[190:191]
	global_store_dwordx4 v136, v[246:249], s[16:17] offset:0
	s_waitcnt vmcnt(7)
	v_pk_add_f32 v[250:251], v[250:251], v[192:193]
	v_pk_add_f32 v[252:253], v[252:253], v[194:195]
	global_store_dwordx4 v137, v[250:253], s[16:17] offset:0
	ds_write_b128 v138, v[60:63] offset:0
	ds_write_b128 v138, v[56:59] offset:4352
	ds_write_b128 v138, v[52:55] offset:64
	ds_write_b128 v138, v[48:51] offset:4416
	ds_write_b128 v138, v[44:47] offset:128
	ds_write_b128 v138, v[40:43] offset:4480
	ds_write_b128 v138, v[36:39] offset:192
	ds_write_b128 v138, v[32:35] offset:4544
	global_load_dwordx4 v[164:167], v130, s[14:15] offset:512
	global_load_dwordx4 v[168:171], v131, s[14:15] offset:512
	global_load_dwordx4 v[172:175], v132, s[14:15] offset:512
	global_load_dwordx4 v[176:179], v133, s[14:15] offset:512
	global_load_dwordx4 v[180:183], v134, s[14:15] offset:512
	global_load_dwordx4 v[184:187], v135, s[14:15] offset:512
	global_load_dwordx4 v[188:191], v136, s[14:15] offset:512
	global_load_dwordx4 v[192:195], v137, s[14:15] offset:512
	ds_read_b128 v[222:225], v139 offset:0
	ds_read_b128 v[226:229], v139 offset:1088
	ds_read_b128 v[230:233], v139 offset:2176
	ds_read_b128 v[234:237], v139 offset:3264
	ds_read_b128 v[238:241], v139 offset:4352
	ds_read_b128 v[242:245], v139 offset:5440
	ds_read_b128 v[246:249], v139 offset:6528
	ds_read_b128 v[250:253], v139 offset:7616
	s_waitcnt lgkmcnt(0)
	s_waitcnt vmcnt(7)
	v_pk_add_f32 v[222:223], v[222:223], v[164:165]
	v_pk_add_f32 v[224:225], v[224:225], v[166:167]
	global_store_dwordx4 v130, v[222:225], s[16:17] offset:512
	s_waitcnt vmcnt(7)
	v_pk_add_f32 v[226:227], v[226:227], v[168:169]
	v_pk_add_f32 v[228:229], v[228:229], v[170:171]
	global_store_dwordx4 v131, v[226:229], s[16:17] offset:512
	s_waitcnt vmcnt(7)
	v_pk_add_f32 v[230:231], v[230:231], v[172:173]
	v_pk_add_f32 v[232:233], v[232:233], v[174:175]
	global_store_dwordx4 v132, v[230:233], s[16:17] offset:512
	s_waitcnt vmcnt(7)
	v_pk_add_f32 v[234:235], v[234:235], v[176:177]
	v_pk_add_f32 v[236:237], v[236:237], v[178:179]
	global_store_dwordx4 v133, v[234:237], s[16:17] offset:512
	s_waitcnt vmcnt(7)
; #define SCHED __builtin_amdgcn_sched_barrier(0)
; __device__ __forceinline__ void phase_gemm2(const Params& p, int layer, const float* xold, float* xnew) {
;     ...
;   for (int tile = blockIdx.x; tile < nA * nB; tile += gridDim.x) {
;     ...
; #pragma unroll
;     for (int ai = 0; ai < 2; ++ai)
; #pragma unroll
;       for (int bj = 0; bj < 2; ++bj) {
;         f32x4 xo[4][2];
; #pragma unroll
;         for (int m = 0; m < 4; ++m)
; #pragma unroll
;           for (int n = 0; n < 2; ++n) {
;             int feat = feat0 + ai * 128 + wr * 64 + m * 16 + fq * 4;
;             int tok = tok0 + bj * 128 + wc * 32 + n * 16 + fr;
;             xo[m][n] = *reinterpret_cast<const f32x4*>(xold + (size_t)tok * DM + feat);
;           }
;         SCHED;
; #pragma unroll
;         for (int m = 0; m < 4; ++m)
; #pragma unroll
;           for (int n = 0; n < 2; ++n) {
;             int feat = feat0 + ai * 128 + wr * 64 + m * 16 + fq * 4;
;             int tok = tok0 + bj * 128 + wc * 32 + n * 16 + fr;
;             *reinterpret_cast<f32x4*>(xnew + (size_t)tok * DM + feat) = xo[m][n] + acc[ai][bj][m][n];
;           }
;         SCHED;
;       }
	v_pk_add_f32 v[238:239], v[238:239], v[180:181]
	v_pk_add_f32 v[240:241], v[240:241], v[182:183]
	global_store_dwordx4 v134, v[238:241], s[16:17] offset:512
	s_waitcnt vmcnt(7)
	v_pk_add_f32 v[242:243], v[242:243], v[184:185]
	v_pk_add_f32 v[244:245], v[244:245], v[186:187]
	global_store_dwordx4 v135, v[242:245], s[16:17] offset:512
	s_waitcnt vmcnt(7)
	v_pk_add_f32 v[246:247], v[246:247], v[188:189]
	v_pk_add_f32 v[248:249], v[248:249], v[190:191]
	global_store_dwordx4 v136, v[246:249], s[16:17] offset:512
	s_waitcnt vmcnt(7)
	v_pk_add_f32 v[250:251], v[250:251], v[192:193]
	v_pk_add_f32 v[252:253], v[252:253], v[194:195]
	global_store_dwordx4 v137, v[250:253], s[16:17] offset:512
	s_add_u32 s14, s8, 0x200000
	s_addc_u32 s15, s9, 0
	s_add_u32 s16, s10, 0x200000
	s_addc_u32 s17, s11, 0
	ds_write_b128 v138, v[92:95] offset:0
	ds_write_b128 v138, v[88:91] offset:4352
	ds_write_b128 v138, v[84:87] offset:64
	ds_write_b128 v138, v[80:83] offset:4416
	ds_write_b128 v138, v[76:79] offset:128
	ds_write_b128 v138, v[72:75] offset:4480
	ds_write_b128 v138, v[68:71] offset:192
	ds_write_b128 v138, v[64:67] offset:4544
	global_load_dwordx4 v[164:167], v130, s[14:15] offset:0
	global_load_dwordx4 v[168:171], v131, s[14:15] offset:0
	global_load_dwordx4 v[172:175], v132, s[14:15] offset:0
	global_load_dwordx4 v[176:179], v133, s[14:15] offset:0
	global_load_dwordx4 v[180:183], v134, s[14:15] offset:0
	global_load_dwordx4 v[184:187], v135, s[14:15] offset:0
	global_load_dwordx4 v[188:191], v136, s[14:15] offset:0
	global_load_dwordx4 v[192:195], v137, s[14:15] offset:0
	ds_read_b128 v[222:225], v139 offset:0
	ds_read_b128 v[226:229], v139 offset:1088
	ds_read_b128 v[230:233], v139 offset:2176
	ds_read_b128 v[234:237], v139 offset:3264
	ds_read_b128 v[238:241], v139 offset:4352
	ds_read_b128 v[242:245], v139 offset:5440
	ds_read_b128 v[246:249], v139 offset:6528
	ds_read_b128 v[250:253], v139 offset:7616
	s_waitcnt lgkmcnt(0)
	s_waitcnt vmcnt(7)
	v_pk_add_f32 v[222:223], v[222:223], v[164:165]
	v_pk_add_f32 v[224:225], v[224:225], v[166:167]
	global_store_dwordx4 v130, v[222:225], s[16:17] offset:0
	s_waitcnt vmcnt(7)
	v_pk_add_f32 v[226:227], v[226:227], v[168:169]
	v_pk_add_f32 v[228:229], v[228:229], v[170:171]
	global_store_dwordx4 v131, v[226:229], s[16:17] offset:0
	s_waitcnt vmcnt(7)
	v_pk_add_f32 v[230:231], v[230:231], v[172:173]
	v_pk_add_f32 v[232:233], v[232:233], v[174:175]
	global_store_dwordx4 v132, v[230:233], s[16:17] offset:0
	s_waitcnt vmcnt(7)
	v_pk_add_f32 v[234:235], v[234:235], v[176:177]
	v_pk_add_f32 v[236:237], v[236:237], v[178:179]
	global_store_dwordx4 v133, v[234:237], s[16:17] offset:0
	s_waitcnt vmcnt(7)
	v_pk_add_f32 v[238:239], v[238:239], v[180:181]
	v_pk_add_f32 v[240:241], v[240:241], v[182:183]
	global_store_dwordx4 v134, v[238:241], s[16:17] offset:0
	s_waitcnt vmcnt(7)
	v_pk_add_f32 v[242:243], v[242:243], v[184:185]
	v_pk_add_f32 v[244:245], v[244:245], v[186:187]
	global_store_dwordx4 v135, v[242:245], s[16:17] offset:0
	s_waitcnt vmcnt(7)
	v_pk_add_f32 v[246:247], v[246:247], v[188:189]
	v_pk_add_f32 v[248:249], v[248:249], v[190:191]
	global_store_dwordx4 v136, v[246:249], s[16:17] offset:0
	s_waitcnt vmcnt(7)
	v_pk_add_f32 v[250:251], v[250:251], v[192:193]
	v_pk_add_f32 v[252:253], v[252:253], v[194:195]
	global_store_dwordx4 v137, v[250:253], s[16:17] offset:0
	ds_write_b128 v138, v[28:31] offset:0
	ds_write_b128 v138, v[24:27] offset:4352
	ds_write_b128 v138, v[20:23] offset:64
	ds_write_b128 v138, v[16:19] offset:4416
	ds_write_b128 v138, v[12:15] offset:128
	ds_write_b128 v138, v[8:11] offset:4480
	ds_write_b128 v138, v[4:7] offset:192
	ds_write_b128 v138, v[0:3] offset:4544
	global_load_dwordx4 v[164:167], v130, s[14:15] offset:512
	global_load_dwordx4 v[168:171], v131, s[14:15] offset:512
	global_load_dwordx4 v[172:175], v132, s[14:15] offset:512
	global_load_dwordx4 v[176:179], v133, s[14:15] offset:512
	global_load_dwordx4 v[180:183], v134, s[14:15] offset:512
	global_load_dwordx4 v[184:187], v135, s[14:15] offset:512
	global_load_dwordx4 v[188:191], v136, s[14:15] offset:512
	global_load_dwordx4 v[192:195], v137, s[14:15] offset:512
	ds_read_b128 v[222:225], v139 offset:0
	ds_read_b128 v[226:229], v139 offset:1088
	ds_read_b128 v[230:233], v139 offset:2176
	ds_read_b128 v[234:237], v139 offset:3264
	ds_read_b128 v[238:241], v139 offset:4352
	ds_read_b128 v[242:245], v139 offset:5440
	ds_read_b128 v[246:249], v139 offset:6528
	ds_read_b128 v[250:253], v139 offset:7616
	s_waitcnt lgkmcnt(0)
	s_waitcnt vmcnt(7)
	v_pk_add_f32 v[222:223], v[222:223], v[164:165]
	v_pk_add_f32 v[224:225], v[224:225], v[166:167]
	global_store_dwordx4 v130, v[222:225], s[16:17] offset:512
	s_waitcnt vmcnt(7)
	v_pk_add_f32 v[226:227], v[226:227], v[168:169]
	v_pk_add_f32 v[228:229], v[228:229], v[170:171]
	global_store_dwordx4 v131, v[226:229], s[16:17] offset:512
	s_waitcnt vmcnt(7)
	v_pk_add_f32 v[230:231], v[230:231], v[172:173]
	v_pk_add_f32 v[232:233], v[232:233], v[174:175]
	global_store_dwordx4 v132, v[230:233], s[16:17] offset:512
	s_waitcnt vmcnt(7)
	v_pk_add_f32 v[234:235], v[234:235], v[176:177]
	v_pk_add_f32 v[236:237], v[236:237], v[178:179]
	global_store_dwordx4 v133, v[234:237], s[16:17] offset:512
	s_waitcnt vmcnt(7)
	v_pk_add_f32 v[238:239], v[238:239], v[180:181]
	v_pk_add_f32 v[240:241], v[240:241], v[182:183]
	global_store_dwordx4 v134, v[238:241], s[16:17] offset:512
	s_waitcnt vmcnt(7)
	v_pk_add_f32 v[242:243], v[242:243], v[184:185]
	v_pk_add_f32 v[244:245], v[244:245], v[186:187]
	global_store_dwordx4 v135, v[242:245], s[16:17] offset:512
	s_waitcnt vmcnt(7)
	v_pk_add_f32 v[246:247], v[246:247], v[188:189]
	v_pk_add_f32 v[248:249], v[248:249], v[190:191]
	global_store_dwordx4 v136, v[246:249], s[16:17] offset:512
	s_waitcnt vmcnt(7)
	v_pk_add_f32 v[250:251], v[250:251], v[192:193]
	v_pk_add_f32 v[252:253], v[252:253], v[194:195]
	global_store_dwordx4 v137, v[250:253], s[16:17] offset:512
	s_load_dword s14, s[48:49], 0x0
	s_waitcnt lgkmcnt(0)
	s_add_i32 s30, s14, s30
	s_cmpk_gt_i32 s30, 0x1ff
	s_cbranch_scc1 .LBB0_47
